# final_norm gain loads hoisted out of loop; scan step: first LDS fragment reads issued before prefetch address calc
# speedup vs baseline: 1.0120x; 1.0030x over previous
.LBB0_1472:
	v_add_u32_e32 v174, v166, v160
	v_add_u32_e32 v175, v167, v160
	ds_read_b128 v[52:55], v132
	ds_read_b128 v[60:63], v174 offset:17408
	ds_read_b128 v[64:67], v175 offset:17408
	v_add_u32_e32 v173, v161, v160
	ds_read_b128 v[56:59], v173
	ds_read_b128 v[68:71], v133
	ds_read_b128 v[72:75], v174 offset:17472
	s_cmp_gt_u32 s64, 3
	s_mov_b64 s[0:1], -1
	s_cbranch_scc0 .LBB0_1476
	s_add_i32 s2, s41, 1
	s_add_i32 s3, s64, -4
	s_and_b64 s[0:1], s[74:75], exec
	s_cselect_b32 s0, s3, s2
	s_add_i32 s63, s0, s93
	s_cbranch_execz .LBB0_1477

.LBB0_1480:
	s_lshl_b32 s0, s2, 2
	s_or_b32 s0, s0, s73
	s_ashr_i32 s1, s0, 31
	s_lshl_b32 s65, s2, 6
	s_lshl_b64 s[2:3], s[0:1], 14
	v_lshl_add_u64 v[36:37], v[112:113], 0, s[2:3]
	v_lshl_add_u64 v[40:41], v[108:109], 0, s[2:3]
	s_lshl_b64 s[2:3], s[0:1], 15
	s_add_u32 s2, s30, s2
	s_addc_u32 s3, s40, s3
	v_add_u32_e32 v16, s65, v145
	v_add_u32_e32 v28, s65, v147
	v_lshl_add_u64 v[44:45], v[106:107], 1, s[2:3]
	v_ashrrev_i32_e32 v17, 31, v16
	v_ashrrev_i32_e32 v29, 31, v28
	v_lshl_add_u64 v[44:45], v[44:45], 0, v[176:177]
	v_lshlrev_b64 v[20:21], 10, v[16:17]
	v_lshlrev_b64 v[32:33], 10, v[28:29]
	v_add_co_u32_e32 v48, vcc, 0x2000, v44
	v_lshl_add_u64 v[16:17], v[98:99], 0, v[20:21]
	v_lshl_add_u64 v[20:21], v[100:101], 0, v[20:21]
	v_lshl_add_u64 v[24:25], v[102:103], 1, v[36:37]
	v_lshl_add_u64 v[28:29], v[98:99], 0, v[32:33]
	v_lshl_add_u64 v[32:33], v[100:101], 0, v[32:33]
	v_lshl_add_u64 v[36:37], v[104:105], 1, v[36:37]
	v_addc_co_u32_e32 v49, vcc, 0, v45, vcc
	global_load_dwordx4 v[16:19], v[16:17], off
	s_nop 0
	global_load_dwordx4 v[20:23], v[20:21], off
	s_nop 0
	global_load_dwordx4 v[24:27], v[24:25], off
	s_nop 0
	global_load_dwordx4 v[28:31], v[28:29], off
	s_nop 0
	global_load_dwordx4 v[32:35], v[32:33], off
	s_nop 0
	global_load_dwordx4 v[36:39], v[36:37], off
	s_nop 0
	global_load_dwordx4 v[40:43], v[40:41], off
	s_nop 0
	global_load_dwordx4 v[44:47], v[44:45], off
	s_nop 0
	global_load_dwordx4 v[48:51], v[48:49], off
	s_and_saveexec_b64 s[2:3], s[60:61]
	s_cbranch_execz .LBB0_1482
	s_lshl_b64 s[0:1], s[0:1], 9
	v_lshl_add_u64 v[88:89], v[114:115], 0, s[0:1]
	global_load_dword v149, v[88:89], off
.LBB0_1482:
	s_or_b64 exec, exec, s[2:3]
	s_bitcmp0_b32 s64, 0
	s_waitcnt lgkmcnt(0)
	v_mfma_f32_16x16x32_bf16 v[52:55], v[52:55], v[56:59], 0
	s_cselect_b64 s[0:1], -1, 0
	s_and_b64 s[2:3], s[0:1], exec
	s_mov_b32 s2, 0x23100
	v_mfma_f32_16x16x32_bf16 v[60:63], v[60:63], v[56:59], 0
	s_cselect_b32 s3, 0x8800, s2
	s_cselect_b32 s2, s89, 0x27900
	s_add_i32 s64, s77, s2
	v_mfma_f32_16x16x32_bf16 v[64:67], v[64:67], v[56:59], 0
	v_mfma_f32_16x16x32_bf16 v[56:59], v[68:71], v[56:59], 0
	ds_read_b128 v[68:71], v173 offset:64
	ds_read_b128 v[76:79], v132 offset:64
	s_waitcnt lgkmcnt(0)
	v_mfma_f32_16x16x32_bf16 v[60:63], v[72:75], v[68:71], v[60:63]
	ds_read_b128 v[72:75], v175 offset:17472
	v_mfma_f32_16x16x32_bf16 v[52:55], v[76:79], v[68:71], v[52:55]
	ds_read_b128 v[76:79], v133 offset:64
	s_waitcnt lgkmcnt(0)
	v_mfma_f32_16x16x32_bf16 v[64:67], v[72:75], v[68:71], v[64:67]
	ds_read_b128 v[72:75], v174 offset:17536
	ds_read_b128 v[80:83], v173 offset:128
	v_mfma_f32_16x16x32_bf16 v[56:59], v[76:79], v[68:71], v[56:59]
	ds_read_b128 v[68:71], v132 offset:128
	s_waitcnt lgkmcnt(0)
	v_mfma_f32_16x16x32_bf16 v[60:63], v[72:75], v[80:83], v[60:63]
	ds_read_b128 v[72:75], v175 offset:17536
	v_mfma_f32_16x16x32_bf16 v[52:55], v[68:71], v[80:83], v[52:55]
	ds_read_b128 v[68:71], v133 offset:128
	s_waitcnt lgkmcnt(0)
	v_mfma_f32_16x16x32_bf16 v[72:75], v[72:75], v[80:83], v[64:67]
	s_nop 2
	ds_read_b128 v[64:67], v174 offset:17600
	ds_read_b128 v[76:79], v173 offset:192
	v_mfma_f32_16x16x32_bf16 v[56:59], v[68:71], v[80:83], v[56:59]
	ds_read_b128 v[68:71], v132 offset:192
	ds_read_b128 v[80:83], v175 offset:17600
	ds_read_b128 v[84:87], v133 offset:192
	s_waitcnt lgkmcnt(0)
	v_mfma_f32_16x16x32_bf16 v[52:55], v[68:71], v[76:79], v[52:55]
	v_mov_b32_e32 v68, s64
	ds_read_b32 v194, v68
	v_mfma_f32_16x16x32_bf16 v[64:67], v[64:67], v[76:79], v[60:63]
	v_mfma_f32_16x16x32_bf16 v[60:63], v[80:83], v[76:79], v[72:75]
	v_mfma_f32_16x16x32_bf16 v[56:59], v[84:87], v[76:79], v[56:59]
	v_add_u32_e32 v193, s3, v172
	ds_read_b128 v[68:71], v193
	v_add_u32_e32 v190, v110, v160
	ds_read_b128 v[72:75], v193 offset:2304
	ds_read_b128 v[76:79], v190 offset:62464
	ds_read_b128 v[80:83], v193 offset:4608
	ds_read_b128 v[84:87], v193 offset:6912
	v_add_u32_e32 v192, v168, v160
	s_waitcnt lgkmcnt(0)
	v_mfma_f32_16x16x32_bf16 v[72:75], v[72:75], v[76:79], 0
	v_add_u32_e32 v188, v169, v160
	v_add_u32_e32 v195, s2, v96
	s_add_i32 s64, s2, 0
	v_mfma_f32_16x16x32_bf16 v[88:91], v[80:83], v[76:79], 0
	ds_read_b128 v[80:83], v159
	v_mfma_f32_16x16x32_bf16 v[68:71], v[68:71], v[76:79], 0
	v_mfma_f32_16x16x32_bf16 v[196:199], v[84:87], v[76:79], 0
	ds_read_b128 v[76:79], v192 offset:53248
	ds_read_b128 v[84:87], v188 offset:53248
	s_waitcnt lgkmcnt(0)
	v_mfma_f32_16x16x32_bf16 v[200:203], v[80:83], v[76:79], 0
	ds_read_b128 v[76:79], v193 offset:64
	ds_read_b128 v[222:225], v190 offset:62528
	v_mfma_f32_16x16x32_bf16 v[226:229], v[80:83], v[84:87], 0
	ds_read_b128 v[80:83], v193 offset:2368
	s_waitcnt lgkmcnt(0)
	v_mfma_f32_16x16x32_bf16 v[76:79], v[76:79], v[222:225], v[68:71]
	s_nop 2
	ds_read_b128 v[68:71], v193 offset:4672
	s_waitcnt lgkmcnt(0)
	v_mfma_f32_16x16x32_bf16 v[84:87], v[68:71], v[222:225], v[88:91]
	ds_read_b128 v[68:71], v159 offset:64
	v_mfma_f32_16x16x32_bf16 v[80:83], v[80:83], v[222:225], v[72:75]
	s_nop 2
	ds_read_b128 v[72:75], v193 offset:6976
	s_waitcnt lgkmcnt(0)
	v_mfma_f32_16x16x32_bf16 v[88:91], v[72:75], v[222:225], v[196:199]
	ds_read_b128 v[72:75], v192 offset:53312
	ds_read_b128 v[222:225], v188 offset:53312
	s_nop 0
	ds_read_b32 v196, v195
	v_mov_b32_e32 v197, 0
	s_waitcnt lgkmcnt(0)
	v_mfma_f32_16x16x32_bf16 v[72:75], v[68:71], v[72:75], v[200:203]
	v_mov_b32_e32 v198, 0
	v_mfma_f32_16x16x32_bf16 v[68:71], v[68:71], v[222:225], v[226:229]
	s_and_saveexec_b64 s[2:3], s[58:59]
	s_cbranch_execz .LBB0_1496
	v_add_u32_e32 v180, s64, v143
	ds_read_b32 v180, v180
	s_waitcnt lgkmcnt(0)
	v_sub_f32_e32 v180, v196, v180
	v_mul_f32_e32 v180, 0x3fb8aa3b, v180
	v_exp_f32_e32 v180, v180
	s_nop 0
	v_mul_f32_e32 v198, v64, v180
	s_or_b64 exec, exec, s[2:3]
	v_mov_b32_e32 v199, 0
	s_and_saveexec_b64 s[2:3], s[56:57]
	s_cbranch_execnz .LBB0_1497

.LBB0_2737:
	s_add_i32 s0, 0, 0x27fe0
	v_mov_b32_e32 v0, s0
	ds_read_b32 v0, v0
	s_add_i32 s0, 0, 0x27fe4
	v_mov_b32_e32 v1, s0
	ds_read_b32 v1, v1
	s_waitcnt lgkmcnt(0)
	v_readfirstlane_b32 s0, v0
	v_ashrrev_i32_e32 v0, 6, v179
	v_add_u32_e32 v0, s85, v0
	s_mov_b32 s2, 0x8000
	v_readfirstlane_b32 s1, v1
	v_cmp_gt_i32_e32 vcc, s2, v0
	s_and_saveexec_b64 s[2:3], vcc
	v_readlane_b32 s8, v254, 33
	v_readlane_b32 s9, v254, 34
	s_cbranch_execz .LBB0_2740
	v_and_b32_e32 v1, 64, v208
	v_add_u32_e32 v1, 64, v1
	v_xor_b32_e32 v4, 32, v208
	v_cmp_lt_i32_e32 vcc, v4, v1
	v_lshlrev_b32_e32 v2, 4, v179
	v_and_b32_e32 v2, 0x3f0, v2
	v_cndmask_b32_e32 v4, v208, v4, vcc
	v_lshlrev_b32_e32 v6, 2, v4
	v_xor_b32_e32 v4, 16, v208
	v_cmp_lt_i32_e32 vcc, v4, v1
	v_mov_b32_e32 v3, 0
	s_ashr_i32 s9, s8, 31
	v_cndmask_b32_e32 v4, v208, v4, vcc
	v_lshlrev_b32_e32 v7, 2, v4
	v_xor_b32_e32 v4, 8, v208
	v_cmp_lt_i32_e32 vcc, v4, v1
	v_lshl_add_u64 v[2:3], s[14:15], 0, v[2:3]
	s_lshl_b64 s[2:3], s[8:9], 12
	v_cndmask_b32_e32 v4, v208, v4, vcc
	v_lshlrev_b32_e32 v8, 2, v4
	v_xor_b32_e32 v4, 4, v208
	v_cmp_lt_i32_e32 vcc, v4, v1
	s_mov_b64 s[4:5], 0
	s_mov_b32 s6, 0x800000
	v_cndmask_b32_e32 v4, v208, v4, vcc
	v_lshlrev_b32_e32 v9, 2, v4
	v_xor_b32_e32 v4, 2, v208
	v_cmp_lt_i32_e32 vcc, v4, v1
	s_movk_i32 s7, 0x7fff
	s_nop 0
	v_cndmask_b32_e32 v4, v208, v4, vcc
	v_lshlrev_b32_e32 v10, 2, v4
	v_xor_b32_e32 v4, 1, v208
	v_cmp_lt_i32_e32 vcc, v4, v1
	s_nop 1
	v_cndmask_b32_e32 v1, v208, v4, vcc
	v_lshlrev_b32_e32 v11, 2, v1
	v_ashrrev_i32_e32 v1, 31, v0
	v_lshlrev_b64 v[4:5], 12, v[0:1]
	v_and_b32_e32 v1, 63, v179
	v_lshl_or_b32 v4, v1, 4, v4
	v_mov_b32_e32 v1, 0x358637bd
	global_load_dwordx4 v[60:63], v[2:3], off offset:1024
	global_load_dwordx4 v[64:67], v[2:3], off offset:2048
	global_load_dwordx4 v[68:71], v[2:3], off offset:3072
.LBB0_2739:
	v_lshl_add_u64 v[32:33], s[0:1], 0, v[4:5]
	flat_load_dwordx4 v[12:15], v[32:33]
	flat_load_dwordx4 v[16:19], v[32:33] offset:1024
	flat_load_dwordx4 v[20:23], v[32:33] offset:2048
	flat_load_dwordx4 v[24:27], v[32:33] offset:3072
	global_load_dwordx4 v[28:31], v[2:3], off
	v_lshl_add_u64 v[32:33], s[16:17], 0, v[4:5]
	v_add_u32_e32 v0, s8, v0
	v_lshl_add_u64 v[4:5], v[4:5], 0, s[2:3]
	s_waitcnt vmcnt(0) lgkmcnt(0)
	v_mov_b32_e32 v36, v13
	v_mov_b32_e32 v37, v17
	v_mov_b32_e32 v34, v12
	v_mov_b32_e32 v35, v16
	v_mov_b32_e32 v44, v21
	v_mov_b32_e32 v45, v25
	v_pk_mul_f32 v[36:37], v[36:37], v[36:37]
	v_mov_b32_e32 v38, v14
	v_mov_b32_e32 v39, v18
	v_mov_b32_e32 v42, v20
	v_mov_b32_e32 v43, v24
	v_pk_mul_f32 v[44:45], v[44:45], v[44:45]
	v_pk_fma_f32 v[34:35], v[34:35], v[34:35], v[36:37]
	v_mov_b32_e32 v40, v15
	v_mov_b32_e32 v41, v19
	v_mov_b32_e32 v46, v22
	v_mov_b32_e32 v47, v26
	v_pk_fma_f32 v[36:37], v[42:43], v[42:43], v[44:45]
	v_pk_fma_f32 v[34:35], v[38:39], v[38:39], v[34:35]
	v_mov_b32_e32 v48, v23
	v_mov_b32_e32 v49, v27
	v_pk_fma_f32 v[36:37], v[46:47], v[46:47], v[36:37]
	v_pk_fma_f32 v[34:35], v[40:41], v[40:41], v[34:35]
	v_pk_fma_f32 v[36:37], v[48:49], v[48:49], v[36:37]
	v_add_f32_e32 v34, v34, v35
	v_add_f32_e32 v34, v34, v36
	v_add_f32_e32 v34, v34, v37
	ds_bpermute_b32 v35, v6, v34
	s_waitcnt lgkmcnt(0)
	v_add_f32_e32 v34, v34, v35
	ds_bpermute_b32 v35, v7, v34
	s_waitcnt lgkmcnt(0)
	v_add_f32_e32 v34, v34, v35
	ds_bpermute_b32 v35, v8, v34
	s_waitcnt lgkmcnt(0)
	v_add_f32_e32 v34, v34, v35
	ds_bpermute_b32 v35, v9, v34
	s_waitcnt lgkmcnt(0)
	v_add_f32_e32 v34, v34, v35
	ds_bpermute_b32 v35, v10, v34
	s_waitcnt lgkmcnt(0)
	v_add_f32_e32 v34, v34, v35
	ds_bpermute_b32 v35, v11, v34
	s_waitcnt lgkmcnt(0)
	v_add_f32_e32 v34, v34, v35
	v_fmamk_f32 v34, v34, 0x3a800000, v1
	v_mul_f32_e32 v35, 0x4b800000, v34
	v_cmp_gt_f32_e32 vcc, s6, v34
	s_nop 1
	v_cndmask_b32_e32 v34, v34, v35, vcc
	v_rsq_f32_e32 v34, v34
	s_nop 0
	v_mul_f32_e32 v35, 0x45800000, v34
	v_cndmask_b32_e32 v34, v34, v35, vcc
	v_pk_mul_f32 v[12:13], v[12:13], v[34:35] op_sel_hi:[1,0]
	v_pk_mul_f32 v[14:15], v[14:15], v[34:35] op_sel_hi:[1,0]
	v_pk_mul_f32 v[12:13], v[28:29], v[12:13]
	v_pk_mul_f32 v[14:15], v[30:31], v[14:15]
	global_store_dwordx4 v[32:33], v[12:15], off
	s_nop 1
	v_mov_b64_e32 v[12:13], v[60:61]
	v_mov_b64_e32 v[14:15], v[62:63]
	v_pk_mul_f32 v[18:19], v[18:19], v[34:35] op_sel_hi:[1,0]
	v_pk_mul_f32 v[16:17], v[16:17], v[34:35] op_sel_hi:[1,0]
	v_cmp_lt_i32_e32 vcc, s7, v0
	s_or_b64 s[4:5], vcc, s[4:5]
	s_waitcnt vmcnt(0)
	v_pk_mul_f32 v[12:13], v[12:13], v[16:17]
	v_pk_mul_f32 v[14:15], v[14:15], v[18:19]
	global_store_dwordx4 v[32:33], v[12:15], off offset:1024
	s_nop 1
	v_mov_b64_e32 v[12:13], v[64:65]
	v_mov_b64_e32 v[14:15], v[66:67]
	v_pk_mul_f32 v[16:17], v[22:23], v[34:35] op_sel_hi:[1,0]
	v_pk_mul_f32 v[18:19], v[20:21], v[34:35] op_sel_hi:[1,0]
	s_waitcnt vmcnt(0)
	v_pk_mul_f32 v[14:15], v[14:15], v[16:17]
	v_pk_mul_f32 v[12:13], v[12:13], v[18:19]
	global_store_dwordx4 v[32:33], v[12:15], off offset:2048
	s_nop 1
	v_mov_b64_e32 v[12:13], v[68:69]
	v_mov_b64_e32 v[14:15], v[70:71]
	v_pk_mul_f32 v[16:17], v[26:27], v[34:35] op_sel_hi:[1,0]
	v_pk_mul_f32 v[18:19], v[24:25], v[34:35] op_sel_hi:[1,0]
	s_waitcnt vmcnt(0)
	v_pk_mul_f32 v[14:15], v[14:15], v[16:17]
	v_pk_mul_f32 v[12:13], v[12:13], v[18:19]
	global_store_dwordx4 v[32:33], v[12:15], off offset:3072
	s_andn2_b64 exec, exec, s[4:5]
	s_cbranch_execnz .LBB0_2739
